# scan_rwkv scanner waves: direct path from the end of a 16-step prompt segment to the next segment's operand reads (loop-carried counters updated in place, no address recomputation) for the 126 middle
# baseline (speedup 1.0000x reference)
.LBB0_1632:
	s_andn2_b64 vcc, exec, s[34:35]
	s_movk_i32 s2, 0x700
	s_cbranch_vccnz .LBB0_1634
	s_movk_i32 s2, 0xf00
	v_add_f32_dpp v234, v63, v63 quad_perm:[1,0,3,2] row_mask:0xf bank_mask:0xf bound_ctrl:1
	v_mov_b32_e32 v240, v53
	s_nop 0
	v_add_f32_dpp v234, v234, v234 quad_perm:[2,3,0,1] row_mask:0xf bank_mask:0xf bound_ctrl:1
	s_nop 1
	v_add_f32_dpp v234, v234, v234 row_half_mirror row_mask:0xf bank_mask:0xf bound_ctrl:1
	s_nop 1
	v_add_f32_dpp v234, v234, v234 row_mirror row_mask:0xf bank_mask:0xf bound_ctrl:1
	v_pk_fma_f32 v[36:37], v[32:33], v[234:235], v[54:55] op_sel_hi:[1,0,1]
	v_pk_fma_f32 v[34:35], v[30:31], v[234:235], v[56:57] op_sel_hi:[1,0,1]
	ds_read_b128 v[224:227], v51 offset:3840
	s_waitcnt lgkmcnt(6)
	v_pk_mul_f32 v[232:233], v[28:29], v[36:37]
	v_pk_fma_f32 v[232:233], v[26:27], v[34:35], v[232:233]
	ds_read_b128 v[64:67], v51 offset:3328
	ds_read_b128 v[68:71], v51 offset:3584
	v_add_f32_e32 v234, v232, v233
	v_pk_mul_f32 v[236:237], v[24:25], v[36:37]
	v_pk_fma_f32 v[236:237], v[22:23], v[34:35], v[236:237]
	v_add_f32_dpp v234, v234, v234 quad_perm:[1,0,3,2] row_mask:0xf bank_mask:0xf bound_ctrl:1
	s_waitcnt lgkmcnt(5)
	v_pk_mul_f32 v[228:229], v[18:19], v[34:35]
	v_add_f32_e32 v238, v236, v237
	v_add_f32_dpp v234, v234, v234 quad_perm:[2,3,0,1] row_mask:0xf bank_mask:0xf bound_ctrl:1
	v_pk_mul_f32 v[230:231], v[20:21], v[36:37]
	v_pk_fma_f32 v[56:57], v[14:15], v[240:241], v[228:229] op_sel_hi:[1,0,1]
	v_add_f32_dpp v234, v234, v234 row_half_mirror row_mask:0xf bank_mask:0xf bound_ctrl:1
	v_pk_fma_f32 v[54:55], v[16:17], v[240:241], v[230:231] op_sel_hi:[1,0,1]
	v_add_f32_dpp v238, v238, v238 quad_perm:[1,0,3,2] row_mask:0xf bank_mask:0xf bound_ctrl:1
	v_add_f32_dpp v234, v234, v234 row_mirror row_mask:0xf bank_mask:0xf bound_ctrl:1
	ds_read_b32 v242, v62 offset:4352
	ds_read_b128 v[30:33], v51 offset:4096
	ds_read_b128 v[22:25], v51 offset:3072
	s_waitcnt lgkmcnt(7)
	v_pk_fma_f32 v[36:37], v[12:13], v[234:235], v[54:55] op_sel_hi:[1,0,1]
	v_pk_fma_f32 v[34:35], v[10:11], v[234:235], v[56:57] op_sel_hi:[1,0,1]
	v_add_f32_dpp v238, v238, v238 quad_perm:[2,3,0,1] row_mask:0xf bank_mask:0xf bound_ctrl:1
	ds_write_b32 v49, v238
	ds_read_b128 v[26:29], v51 offset:5376
	s_waitcnt lgkmcnt(6)
	v_pk_mul_f32 v[232:233], v[226:227], v[36:37]
	v_pk_fma_f32 v[232:233], v[224:225], v[34:35], v[232:233]
	ds_read_b128 v[18:21], v51 offset:4864
	ds_read_b128 v[14:17], v51 offset:5120
	v_add_f32_e32 v234, v232, v233
	v_pk_mul_f32 v[236:237], v[8:9], v[36:37]
	v_pk_fma_f32 v[236:237], v[6:7], v[34:35], v[236:237]
	v_add_f32_dpp v234, v234, v234 quad_perm:[1,0,3,2] row_mask:0xf bank_mask:0xf bound_ctrl:1
	s_waitcnt lgkmcnt(5)
	v_pk_mul_f32 v[228:229], v[64:65], v[34:35]
	v_add_f32_e32 v238, v236, v237
	v_add_f32_dpp v234, v234, v234 quad_perm:[2,3,0,1] row_mask:0xf bank_mask:0xf bound_ctrl:1
	v_pk_mul_f32 v[230:231], v[66:67], v[36:37]
	v_pk_fma_f32 v[56:57], v[68:69], v[242:243], v[228:229] op_sel_hi:[1,0,1]
	v_add_f32_dpp v234, v234, v234 row_half_mirror row_mask:0xf bank_mask:0xf bound_ctrl:1
	v_pk_fma_f32 v[54:55], v[70:71], v[242:243], v[230:231] op_sel_hi:[1,0,1]
	v_add_f32_dpp v238, v238, v238 quad_perm:[1,0,3,2] row_mask:0xf bank_mask:0xf bound_ctrl:1
	v_add_f32_dpp v234, v234, v234 row_mirror row_mask:0xf bank_mask:0xf bound_ctrl:1
	ds_read_b32 v240, v62 offset:5888
	ds_read_b128 v[10:13], v51 offset:5632
	ds_read_b128 v[6:9], v51 offset:4608
	s_waitcnt lgkmcnt(7)
	v_pk_fma_f32 v[36:37], v[32:33], v[234:235], v[54:55] op_sel_hi:[1,0,1]
	v_pk_fma_f32 v[34:35], v[30:31], v[234:235], v[56:57] op_sel_hi:[1,0,1]
	v_add_f32_dpp v238, v238, v238 quad_perm:[2,3,0,1] row_mask:0xf bank_mask:0xf bound_ctrl:1
	ds_write_b32 v49, v238 offset:256
	ds_read_b128 v[224:227], v51 offset:6912
	s_waitcnt lgkmcnt(6)
	v_pk_mul_f32 v[232:233], v[28:29], v[36:37]
	v_pk_fma_f32 v[232:233], v[26:27], v[34:35], v[232:233]
	ds_read_b128 v[64:67], v51 offset:6400
	ds_read_b128 v[68:71], v51 offset:6656
	v_add_f32_e32 v234, v232, v233
	v_pk_mul_f32 v[236:237], v[24:25], v[36:37]
	v_pk_fma_f32 v[236:237], v[22:23], v[34:35], v[236:237]
	v_add_f32_dpp v234, v234, v234 quad_perm:[1,0,3,2] row_mask:0xf bank_mask:0xf bound_ctrl:1
	s_waitcnt lgkmcnt(5)
	v_pk_mul_f32 v[228:229], v[18:19], v[34:35]
	v_add_f32_e32 v238, v236, v237
	v_add_f32_dpp v234, v234, v234 quad_perm:[2,3,0,1] row_mask:0xf bank_mask:0xf bound_ctrl:1
	v_pk_mul_f32 v[230:231], v[20:21], v[36:37]
	v_pk_fma_f32 v[56:57], v[14:15], v[240:241], v[228:229] op_sel_hi:[1,0,1]
	v_add_f32_dpp v234, v234, v234 row_half_mirror row_mask:0xf bank_mask:0xf bound_ctrl:1
	v_pk_fma_f32 v[54:55], v[16:17], v[240:241], v[230:231] op_sel_hi:[1,0,1]
	v_add_f32_dpp v238, v238, v238 quad_perm:[1,0,3,2] row_mask:0xf bank_mask:0xf bound_ctrl:1
	v_add_f32_dpp v234, v234, v234 row_mirror row_mask:0xf bank_mask:0xf bound_ctrl:1
	ds_read_b32 v242, v62 offset:7424
	ds_read_b128 v[30:33], v51 offset:7168
	ds_read_b128 v[22:25], v51 offset:6144
	s_waitcnt lgkmcnt(7)
	v_pk_fma_f32 v[36:37], v[12:13], v[234:235], v[54:55] op_sel_hi:[1,0,1]
	v_pk_fma_f32 v[34:35], v[10:11], v[234:235], v[56:57] op_sel_hi:[1,0,1]
	v_add_f32_dpp v238, v238, v238 quad_perm:[2,3,0,1] row_mask:0xf bank_mask:0xf bound_ctrl:1
	ds_write_b32 v49, v238 offset:512
	ds_read_b128 v[26:29], v51 offset:8448
	s_waitcnt lgkmcnt(6)
	v_pk_mul_f32 v[232:233], v[226:227], v[36:37]
	v_pk_fma_f32 v[232:233], v[224:225], v[34:35], v[232:233]
	ds_read_b128 v[18:21], v51 offset:7936
	ds_read_b128 v[14:17], v51 offset:8192
	v_add_f32_e32 v234, v232, v233
	v_pk_mul_f32 v[236:237], v[8:9], v[36:37]
	v_pk_fma_f32 v[236:237], v[6:7], v[34:35], v[236:237]
	v_add_f32_dpp v234, v234, v234 quad_perm:[1,0,3,2] row_mask:0xf bank_mask:0xf bound_ctrl:1
	s_waitcnt lgkmcnt(5)
	v_pk_mul_f32 v[228:229], v[64:65], v[34:35]
	v_add_f32_e32 v238, v236, v237
	v_add_f32_dpp v234, v234, v234 quad_perm:[2,3,0,1] row_mask:0xf bank_mask:0xf bound_ctrl:1
	v_pk_mul_f32 v[230:231], v[66:67], v[36:37]
	v_pk_fma_f32 v[56:57], v[68:69], v[242:243], v[228:229] op_sel_hi:[1,0,1]
	v_add_f32_dpp v234, v234, v234 row_half_mirror row_mask:0xf bank_mask:0xf bound_ctrl:1
	v_pk_fma_f32 v[54:55], v[70:71], v[242:243], v[230:231] op_sel_hi:[1,0,1]
	v_add_f32_dpp v238, v238, v238 quad_perm:[1,0,3,2] row_mask:0xf bank_mask:0xf bound_ctrl:1
	v_add_f32_dpp v234, v234, v234 row_mirror row_mask:0xf bank_mask:0xf bound_ctrl:1
	ds_read_b32 v240, v62 offset:8960
	ds_read_b128 v[10:13], v51 offset:8704
	ds_read_b128 v[6:9], v51 offset:7680
	s_waitcnt lgkmcnt(7)
	v_pk_fma_f32 v[36:37], v[32:33], v[234:235], v[54:55] op_sel_hi:[1,0,1]
	v_pk_fma_f32 v[34:35], v[30:31], v[234:235], v[56:57] op_sel_hi:[1,0,1]
	v_add_f32_dpp v238, v238, v238 quad_perm:[2,3,0,1] row_mask:0xf bank_mask:0xf bound_ctrl:1
	ds_write_b32 v49, v238 offset:768
	ds_read_b128 v[224:227], v51 offset:9984
	s_waitcnt lgkmcnt(6)
	v_pk_mul_f32 v[232:233], v[28:29], v[36:37]
	v_pk_fma_f32 v[232:233], v[26:27], v[34:35], v[232:233]
	ds_read_b128 v[64:67], v51 offset:9472
	ds_read_b128 v[68:71], v51 offset:9728
	v_add_f32_e32 v234, v232, v233
	v_pk_mul_f32 v[236:237], v[24:25], v[36:37]
	v_pk_fma_f32 v[236:237], v[22:23], v[34:35], v[236:237]
	v_add_f32_dpp v234, v234, v234 quad_perm:[1,0,3,2] row_mask:0xf bank_mask:0xf bound_ctrl:1
	s_waitcnt lgkmcnt(5)
	v_pk_mul_f32 v[228:229], v[18:19], v[34:35]
	v_add_f32_e32 v238, v236, v237
	v_add_f32_dpp v234, v234, v234 quad_perm:[2,3,0,1] row_mask:0xf bank_mask:0xf bound_ctrl:1
	v_pk_mul_f32 v[230:231], v[20:21], v[36:37]
	v_pk_fma_f32 v[56:57], v[14:15], v[240:241], v[228:229] op_sel_hi:[1,0,1]
	v_add_f32_dpp v234, v234, v234 row_half_mirror row_mask:0xf bank_mask:0xf bound_ctrl:1
	v_pk_fma_f32 v[54:55], v[16:17], v[240:241], v[230:231] op_sel_hi:[1,0,1]
	v_add_f32_dpp v238, v238, v238 quad_perm:[1,0,3,2] row_mask:0xf bank_mask:0xf bound_ctrl:1
	v_add_f32_dpp v234, v234, v234 row_mirror row_mask:0xf bank_mask:0xf bound_ctrl:1
	ds_read_b32 v242, v62 offset:10496
	ds_read_b128 v[30:33], v51 offset:10240
	ds_read_b128 v[22:25], v51 offset:9216
	s_waitcnt lgkmcnt(7)
	v_pk_fma_f32 v[36:37], v[12:13], v[234:235], v[54:55] op_sel_hi:[1,0,1]
	v_pk_fma_f32 v[34:35], v[10:11], v[234:235], v[56:57] op_sel_hi:[1,0,1]
	v_add_f32_dpp v238, v238, v238 quad_perm:[2,3,0,1] row_mask:0xf bank_mask:0xf bound_ctrl:1
	ds_write_b32 v49, v238 offset:1024
	ds_read_b128 v[26:29], v51 offset:11520
	s_waitcnt lgkmcnt(6)
	v_pk_mul_f32 v[232:233], v[226:227], v[36:37]
	v_pk_fma_f32 v[232:233], v[224:225], v[34:35], v[232:233]
	ds_read_b128 v[18:21], v51 offset:11008
	ds_read_b128 v[14:17], v51 offset:11264
	v_add_f32_e32 v234, v232, v233
	v_pk_mul_f32 v[236:237], v[8:9], v[36:37]
	v_pk_fma_f32 v[236:237], v[6:7], v[34:35], v[236:237]
	v_add_f32_dpp v234, v234, v234 quad_perm:[1,0,3,2] row_mask:0xf bank_mask:0xf bound_ctrl:1
	s_waitcnt lgkmcnt(5)
	v_pk_mul_f32 v[228:229], v[64:65], v[34:35]
	v_add_f32_e32 v238, v236, v237
	v_add_f32_dpp v234, v234, v234 quad_perm:[2,3,0,1] row_mask:0xf bank_mask:0xf bound_ctrl:1
	v_pk_mul_f32 v[230:231], v[66:67], v[36:37]
	v_pk_fma_f32 v[56:57], v[68:69], v[242:243], v[228:229] op_sel_hi:[1,0,1]
	v_add_f32_dpp v234, v234, v234 row_half_mirror row_mask:0xf bank_mask:0xf bound_ctrl:1
	v_pk_fma_f32 v[54:55], v[70:71], v[242:243], v[230:231] op_sel_hi:[1,0,1]
	v_add_f32_dpp v238, v238, v238 quad_perm:[1,0,3,2] row_mask:0xf bank_mask:0xf bound_ctrl:1
	v_add_f32_dpp v234, v234, v234 row_mirror row_mask:0xf bank_mask:0xf bound_ctrl:1
	ds_read_b32 v240, v62 offset:12032
	ds_read_b128 v[10:13], v51 offset:11776
	ds_read_b128 v[6:9], v51 offset:10752
	s_waitcnt lgkmcnt(7)
	v_pk_fma_f32 v[36:37], v[32:33], v[234:235], v[54:55] op_sel_hi:[1,0,1]
	v_pk_fma_f32 v[34:35], v[30:31], v[234:235], v[56:57] op_sel_hi:[1,0,1]
	v_add_f32_dpp v238, v238, v238 quad_perm:[2,3,0,1] row_mask:0xf bank_mask:0xf bound_ctrl:1
	ds_write_b32 v49, v238 offset:1280
	ds_read_b128 v[224:227], v51 offset:13056
	s_waitcnt lgkmcnt(6)
	v_pk_mul_f32 v[232:233], v[28:29], v[36:37]
	v_pk_fma_f32 v[232:233], v[26:27], v[34:35], v[232:233]
	ds_read_b128 v[64:67], v51 offset:12544
	ds_read_b128 v[68:71], v51 offset:12800
	v_add_f32_e32 v234, v232, v233
	v_pk_mul_f32 v[236:237], v[24:25], v[36:37]
	v_pk_fma_f32 v[236:237], v[22:23], v[34:35], v[236:237]
	v_add_f32_dpp v234, v234, v234 quad_perm:[1,0,3,2] row_mask:0xf bank_mask:0xf bound_ctrl:1
	s_waitcnt lgkmcnt(5)
	v_pk_mul_f32 v[228:229], v[18:19], v[34:35]
	v_add_f32_e32 v238, v236, v237
	v_add_f32_dpp v234, v234, v234 quad_perm:[2,3,0,1] row_mask:0xf bank_mask:0xf bound_ctrl:1
	v_pk_mul_f32 v[230:231], v[20:21], v[36:37]
	v_pk_fma_f32 v[56:57], v[14:15], v[240:241], v[228:229] op_sel_hi:[1,0,1]
	v_add_f32_dpp v234, v234, v234 row_half_mirror row_mask:0xf bank_mask:0xf bound_ctrl:1
	v_pk_fma_f32 v[54:55], v[16:17], v[240:241], v[230:231] op_sel_hi:[1,0,1]
	v_add_f32_dpp v238, v238, v238 quad_perm:[1,0,3,2] row_mask:0xf bank_mask:0xf bound_ctrl:1
	v_add_f32_dpp v234, v234, v234 row_mirror row_mask:0xf bank_mask:0xf bound_ctrl:1
	ds_read_b32 v242, v62 offset:13568
	ds_read_b128 v[30:33], v51 offset:13312
	ds_read_b128 v[22:25], v51 offset:12288
	s_waitcnt lgkmcnt(7)
	v_pk_fma_f32 v[36:37], v[12:13], v[234:235], v[54:55] op_sel_hi:[1,0,1]
	v_pk_fma_f32 v[34:35], v[10:11], v[234:235], v[56:57] op_sel_hi:[1,0,1]
	v_add_f32_dpp v238, v238, v238 quad_perm:[2,3,0,1] row_mask:0xf bank_mask:0xf bound_ctrl:1
	ds_write_b32 v49, v238 offset:1536
	ds_read_b128 v[26:29], v51 offset:14592
	s_waitcnt lgkmcnt(6)
	v_pk_mul_f32 v[232:233], v[226:227], v[36:37]
	v_pk_fma_f32 v[232:233], v[224:225], v[34:35], v[232:233]
	ds_read_b128 v[18:21], v51 offset:14080
	ds_read_b128 v[14:17], v51 offset:14336
	v_add_f32_e32 v234, v232, v233
	v_pk_mul_f32 v[236:237], v[8:9], v[36:37]
	v_pk_fma_f32 v[236:237], v[6:7], v[34:35], v[236:237]
	v_add_f32_dpp v234, v234, v234 quad_perm:[1,0,3,2] row_mask:0xf bank_mask:0xf bound_ctrl:1
	s_waitcnt lgkmcnt(5)
	v_pk_mul_f32 v[228:229], v[64:65], v[34:35]
	v_add_f32_e32 v238, v236, v237
	v_add_f32_dpp v234, v234, v234 quad_perm:[2,3,0,1] row_mask:0xf bank_mask:0xf bound_ctrl:1
	v_pk_mul_f32 v[230:231], v[66:67], v[36:37]
	v_pk_fma_f32 v[56:57], v[68:69], v[242:243], v[228:229] op_sel_hi:[1,0,1]
	v_add_f32_dpp v234, v234, v234 row_half_mirror row_mask:0xf bank_mask:0xf bound_ctrl:1
	v_pk_fma_f32 v[54:55], v[70:71], v[242:243], v[230:231] op_sel_hi:[1,0,1]
	v_add_f32_dpp v238, v238, v238 quad_perm:[1,0,3,2] row_mask:0xf bank_mask:0xf bound_ctrl:1
	v_add_f32_dpp v234, v234, v234 row_mirror row_mask:0xf bank_mask:0xf bound_ctrl:1
	ds_read_b32 v240, v62 offset:15104
	ds_read_b128 v[10:13], v51 offset:14848
	ds_read_b128 v[6:9], v51 offset:13824
	s_waitcnt lgkmcnt(7)
	v_pk_fma_f32 v[36:37], v[32:33], v[234:235], v[54:55] op_sel_hi:[1,0,1]
	v_pk_fma_f32 v[34:35], v[30:31], v[234:235], v[56:57] op_sel_hi:[1,0,1]
	v_add_f32_dpp v238, v238, v238 quad_perm:[2,3,0,1] row_mask:0xf bank_mask:0xf bound_ctrl:1
	ds_write_b32 v49, v238 offset:1792
	ds_read_b128 v[224:227], v51 offset:16128
	s_waitcnt lgkmcnt(6)
	v_pk_mul_f32 v[232:233], v[28:29], v[36:37]
	v_pk_fma_f32 v[232:233], v[26:27], v[34:35], v[232:233]
	ds_read_b128 v[64:67], v51 offset:15616
	ds_read_b128 v[68:71], v51 offset:15872
	v_add_f32_e32 v234, v232, v233
	v_pk_mul_f32 v[236:237], v[24:25], v[36:37]
	v_pk_fma_f32 v[236:237], v[22:23], v[34:35], v[236:237]
	v_add_f32_dpp v234, v234, v234 quad_perm:[1,0,3,2] row_mask:0xf bank_mask:0xf bound_ctrl:1
	s_waitcnt lgkmcnt(5)
	v_pk_mul_f32 v[228:229], v[18:19], v[34:35]
	v_add_f32_e32 v238, v236, v237
	v_add_f32_dpp v234, v234, v234 quad_perm:[2,3,0,1] row_mask:0xf bank_mask:0xf bound_ctrl:1
	v_pk_mul_f32 v[230:231], v[20:21], v[36:37]
	v_pk_fma_f32 v[56:57], v[14:15], v[240:241], v[228:229] op_sel_hi:[1,0,1]
	v_add_f32_dpp v234, v234, v234 row_half_mirror row_mask:0xf bank_mask:0xf bound_ctrl:1
	v_pk_fma_f32 v[54:55], v[16:17], v[240:241], v[230:231] op_sel_hi:[1,0,1]
	v_add_f32_dpp v238, v238, v238 quad_perm:[1,0,3,2] row_mask:0xf bank_mask:0xf bound_ctrl:1
	v_add_f32_dpp v234, v234, v234 row_mirror row_mask:0xf bank_mask:0xf bound_ctrl:1
	ds_read_b32 v242, v62 offset:16640
	ds_read_b128 v[30:33], v51 offset:16384
	ds_read_b128 v[22:25], v51 offset:15360
	s_waitcnt lgkmcnt(7)
	v_pk_fma_f32 v[36:37], v[12:13], v[234:235], v[54:55] op_sel_hi:[1,0,1]
	v_pk_fma_f32 v[34:35], v[10:11], v[234:235], v[56:57] op_sel_hi:[1,0,1]
	v_add_f32_dpp v238, v238, v238 quad_perm:[2,3,0,1] row_mask:0xf bank_mask:0xf bound_ctrl:1
	ds_write_b32 v49, v238 offset:2048
	ds_read_b128 v[26:29], v51 offset:17664
	s_waitcnt lgkmcnt(6)
	v_pk_mul_f32 v[232:233], v[226:227], v[36:37]
	v_pk_fma_f32 v[232:233], v[224:225], v[34:35], v[232:233]
	ds_read_b128 v[18:21], v51 offset:17152
	ds_read_b128 v[14:17], v51 offset:17408
	v_add_f32_e32 v234, v232, v233
	v_pk_mul_f32 v[236:237], v[8:9], v[36:37]
	v_pk_fma_f32 v[236:237], v[6:7], v[34:35], v[236:237]
	v_add_f32_dpp v234, v234, v234 quad_perm:[1,0,3,2] row_mask:0xf bank_mask:0xf bound_ctrl:1
	s_waitcnt lgkmcnt(5)
	v_pk_mul_f32 v[228:229], v[64:65], v[34:35]
	v_add_f32_e32 v238, v236, v237
	v_add_f32_dpp v234, v234, v234 quad_perm:[2,3,0,1] row_mask:0xf bank_mask:0xf bound_ctrl:1
	v_pk_mul_f32 v[230:231], v[66:67], v[36:37]
	v_pk_fma_f32 v[56:57], v[68:69], v[242:243], v[228:229] op_sel_hi:[1,0,1]
	v_add_f32_dpp v234, v234, v234 row_half_mirror row_mask:0xf bank_mask:0xf bound_ctrl:1
	v_pk_fma_f32 v[54:55], v[70:71], v[242:243], v[230:231] op_sel_hi:[1,0,1]
	v_add_f32_dpp v238, v238, v238 quad_perm:[1,0,3,2] row_mask:0xf bank_mask:0xf bound_ctrl:1
	v_add_f32_dpp v234, v234, v234 row_mirror row_mask:0xf bank_mask:0xf bound_ctrl:1
	ds_read_b32 v240, v62 offset:18176
	ds_read_b128 v[10:13], v51 offset:17920
	ds_read_b128 v[6:9], v51 offset:16896
	s_waitcnt lgkmcnt(7)
	v_pk_fma_f32 v[36:37], v[32:33], v[234:235], v[54:55] op_sel_hi:[1,0,1]
	v_pk_fma_f32 v[34:35], v[30:31], v[234:235], v[56:57] op_sel_hi:[1,0,1]
	v_add_f32_dpp v238, v238, v238 quad_perm:[2,3,0,1] row_mask:0xf bank_mask:0xf bound_ctrl:1
	ds_write_b32 v49, v238 offset:2304
	ds_read_b128 v[224:227], v51 offset:19200
	s_waitcnt lgkmcnt(6)
	v_pk_mul_f32 v[232:233], v[28:29], v[36:37]
	v_pk_fma_f32 v[232:233], v[26:27], v[34:35], v[232:233]
	ds_read_b128 v[64:67], v51 offset:18688
	ds_read_b128 v[68:71], v51 offset:18944
	v_add_f32_e32 v234, v232, v233
	v_pk_mul_f32 v[236:237], v[24:25], v[36:37]
	v_pk_fma_f32 v[236:237], v[22:23], v[34:35], v[236:237]
	v_add_f32_dpp v234, v234, v234 quad_perm:[1,0,3,2] row_mask:0xf bank_mask:0xf bound_ctrl:1
	s_waitcnt lgkmcnt(5)
	v_pk_mul_f32 v[228:229], v[18:19], v[34:35]
	v_add_f32_e32 v238, v236, v237
	v_add_f32_dpp v234, v234, v234 quad_perm:[2,3,0,1] row_mask:0xf bank_mask:0xf bound_ctrl:1
	v_pk_mul_f32 v[230:231], v[20:21], v[36:37]
	v_pk_fma_f32 v[56:57], v[14:15], v[240:241], v[228:229] op_sel_hi:[1,0,1]
	v_add_f32_dpp v234, v234, v234 row_half_mirror row_mask:0xf bank_mask:0xf bound_ctrl:1
	v_pk_fma_f32 v[54:55], v[16:17], v[240:241], v[230:231] op_sel_hi:[1,0,1]
	v_add_f32_dpp v238, v238, v238 quad_perm:[1,0,3,2] row_mask:0xf bank_mask:0xf bound_ctrl:1
	v_add_f32_dpp v234, v234, v234 row_mirror row_mask:0xf bank_mask:0xf bound_ctrl:1
	ds_read_b32 v242, v62 offset:19712
	ds_read_b128 v[30:33], v51 offset:19456
	ds_read_b128 v[22:25], v51 offset:18432
	s_waitcnt lgkmcnt(7)
	v_pk_fma_f32 v[36:37], v[12:13], v[234:235], v[54:55] op_sel_hi:[1,0,1]
	v_pk_fma_f32 v[34:35], v[10:11], v[234:235], v[56:57] op_sel_hi:[1,0,1]
	v_add_f32_dpp v238, v238, v238 quad_perm:[2,3,0,1] row_mask:0xf bank_mask:0xf bound_ctrl:1
	ds_write_b32 v49, v238 offset:2560
	ds_read_b128 v[26:29], v51 offset:20736
	s_waitcnt lgkmcnt(6)
	v_pk_mul_f32 v[232:233], v[226:227], v[36:37]
	v_pk_fma_f32 v[232:233], v[224:225], v[34:35], v[232:233]
	ds_read_b128 v[18:21], v51 offset:20224
	ds_read_b128 v[14:17], v51 offset:20480
	v_add_f32_e32 v234, v232, v233
	v_pk_mul_f32 v[236:237], v[8:9], v[36:37]
	v_pk_fma_f32 v[236:237], v[6:7], v[34:35], v[236:237]
	v_add_f32_dpp v234, v234, v234 quad_perm:[1,0,3,2] row_mask:0xf bank_mask:0xf bound_ctrl:1
	s_waitcnt lgkmcnt(5)
	v_pk_mul_f32 v[228:229], v[64:65], v[34:35]
	v_add_f32_e32 v238, v236, v237
	v_add_f32_dpp v234, v234, v234 quad_perm:[2,3,0,1] row_mask:0xf bank_mask:0xf bound_ctrl:1
	v_pk_mul_f32 v[230:231], v[66:67], v[36:37]
	v_pk_fma_f32 v[56:57], v[68:69], v[242:243], v[228:229] op_sel_hi:[1,0,1]
	v_add_f32_dpp v234, v234, v234 row_half_mirror row_mask:0xf bank_mask:0xf bound_ctrl:1
	v_pk_fma_f32 v[54:55], v[70:71], v[242:243], v[230:231] op_sel_hi:[1,0,1]
	v_add_f32_dpp v238, v238, v238 quad_perm:[1,0,3,2] row_mask:0xf bank_mask:0xf bound_ctrl:1
	v_add_f32_dpp v234, v234, v234 row_mirror row_mask:0xf bank_mask:0xf bound_ctrl:1
	ds_read_b32 v240, v62 offset:21248
	ds_read_b128 v[10:13], v51 offset:20992
	ds_read_b128 v[6:9], v51 offset:19968
	s_waitcnt lgkmcnt(7)
	v_pk_fma_f32 v[36:37], v[32:33], v[234:235], v[54:55] op_sel_hi:[1,0,1]
	v_pk_fma_f32 v[34:35], v[30:31], v[234:235], v[56:57] op_sel_hi:[1,0,1]
	v_add_f32_dpp v238, v238, v238 quad_perm:[2,3,0,1] row_mask:0xf bank_mask:0xf bound_ctrl:1
	ds_write_b32 v49, v238 offset:2816
	ds_read_b128 v[224:227], v51 offset:22272
	s_waitcnt lgkmcnt(6)
	v_pk_mul_f32 v[232:233], v[28:29], v[36:37]
	v_pk_fma_f32 v[232:233], v[26:27], v[34:35], v[232:233]
	ds_read_b128 v[64:67], v51 offset:21760
	ds_read_b128 v[68:71], v51 offset:22016
	v_add_f32_e32 v234, v232, v233
	v_pk_mul_f32 v[236:237], v[24:25], v[36:37]
	v_pk_fma_f32 v[236:237], v[22:23], v[34:35], v[236:237]
	v_add_f32_dpp v234, v234, v234 quad_perm:[1,0,3,2] row_mask:0xf bank_mask:0xf bound_ctrl:1
	s_waitcnt lgkmcnt(5)
	v_pk_mul_f32 v[228:229], v[18:19], v[34:35]
	v_add_f32_e32 v238, v236, v237
	v_add_f32_dpp v234, v234, v234 quad_perm:[2,3,0,1] row_mask:0xf bank_mask:0xf bound_ctrl:1
	v_pk_mul_f32 v[230:231], v[20:21], v[36:37]
	v_pk_fma_f32 v[56:57], v[14:15], v[240:241], v[228:229] op_sel_hi:[1,0,1]
	v_add_f32_dpp v234, v234, v234 row_half_mirror row_mask:0xf bank_mask:0xf bound_ctrl:1
	v_pk_fma_f32 v[54:55], v[16:17], v[240:241], v[230:231] op_sel_hi:[1,0,1]
	v_add_f32_dpp v238, v238, v238 quad_perm:[1,0,3,2] row_mask:0xf bank_mask:0xf bound_ctrl:1
	v_add_f32_dpp v234, v234, v234 row_mirror row_mask:0xf bank_mask:0xf bound_ctrl:1
	ds_read_b32 v242, v62 offset:22784
	ds_read_b128 v[30:33], v51 offset:22528
	ds_read_b128 v[22:25], v51 offset:21504
	s_waitcnt lgkmcnt(7)
	v_pk_fma_f32 v[36:37], v[12:13], v[234:235], v[54:55] op_sel_hi:[1,0,1]
	v_pk_fma_f32 v[34:35], v[10:11], v[234:235], v[56:57] op_sel_hi:[1,0,1]
	v_add_f32_dpp v238, v238, v238 quad_perm:[2,3,0,1] row_mask:0xf bank_mask:0xf bound_ctrl:1
	ds_write_b32 v49, v238 offset:3072
	ds_read_b128 v[26:29], v51 offset:23808
	s_waitcnt lgkmcnt(6)
	v_pk_mul_f32 v[232:233], v[226:227], v[36:37]
	v_pk_fma_f32 v[232:233], v[224:225], v[34:35], v[232:233]
	ds_read_b128 v[18:21], v51 offset:23296
	ds_read_b128 v[14:17], v51 offset:23552
	v_add_f32_e32 v234, v232, v233
	v_pk_mul_f32 v[236:237], v[8:9], v[36:37]
	v_pk_fma_f32 v[236:237], v[6:7], v[34:35], v[236:237]
	v_add_f32_dpp v234, v234, v234 quad_perm:[1,0,3,2] row_mask:0xf bank_mask:0xf bound_ctrl:1
	s_waitcnt lgkmcnt(5)
	v_pk_mul_f32 v[228:229], v[64:65], v[34:35]
	v_add_f32_e32 v238, v236, v237
	v_add_f32_dpp v234, v234, v234 quad_perm:[2,3,0,1] row_mask:0xf bank_mask:0xf bound_ctrl:1
	v_pk_mul_f32 v[230:231], v[66:67], v[36:37]
	v_pk_fma_f32 v[56:57], v[68:69], v[242:243], v[228:229] op_sel_hi:[1,0,1]
	v_add_f32_dpp v234, v234, v234 row_half_mirror row_mask:0xf bank_mask:0xf bound_ctrl:1
	v_pk_fma_f32 v[54:55], v[70:71], v[242:243], v[230:231] op_sel_hi:[1,0,1]
	v_add_f32_dpp v238, v238, v238 quad_perm:[1,0,3,2] row_mask:0xf bank_mask:0xf bound_ctrl:1
	v_add_f32_dpp v234, v234, v234 row_mirror row_mask:0xf bank_mask:0xf bound_ctrl:1
	ds_read_b32 v240, v62 offset:24320
	ds_read_b128 v[10:13], v51 offset:24064
	ds_read_b128 v[6:9], v51 offset:23040
	s_waitcnt lgkmcnt(7)
	v_pk_fma_f32 v[36:37], v[32:33], v[234:235], v[54:55] op_sel_hi:[1,0,1]
	v_pk_fma_f32 v[34:35], v[30:31], v[234:235], v[56:57] op_sel_hi:[1,0,1]
	v_add_f32_dpp v238, v238, v238 quad_perm:[2,3,0,1] row_mask:0xf bank_mask:0xf bound_ctrl:1
	ds_write_b32 v49, v238 offset:3328
	s_waitcnt lgkmcnt(5)
	v_pk_mul_f32 v[232:233], v[28:29], v[36:37]
	v_pk_fma_f32 v[232:233], v[26:27], v[34:35], v[232:233]
	v_add_f32_e32 v234, v232, v233
	v_pk_mul_f32 v[236:237], v[24:25], v[36:37]
	v_pk_fma_f32 v[236:237], v[22:23], v[34:35], v[236:237]
	v_add_f32_dpp v234, v234, v234 quad_perm:[1,0,3,2] row_mask:0xf bank_mask:0xf bound_ctrl:1
	s_waitcnt lgkmcnt(2)
	v_pk_mul_f32 v[228:229], v[18:19], v[34:35]
	v_add_f32_e32 v238, v236, v237
	v_add_f32_dpp v234, v234, v234 quad_perm:[2,3,0,1] row_mask:0xf bank_mask:0xf bound_ctrl:1
	v_pk_mul_f32 v[230:231], v[20:21], v[36:37]
	v_pk_fma_f32 v[56:57], v[14:15], v[240:241], v[228:229] op_sel_hi:[1,0,1]
	v_add_f32_dpp v234, v234, v234 row_half_mirror row_mask:0xf bank_mask:0xf bound_ctrl:1
	v_pk_fma_f32 v[54:55], v[16:17], v[240:241], v[230:231] op_sel_hi:[1,0,1]
	v_add_f32_dpp v238, v238, v238 quad_perm:[1,0,3,2] row_mask:0xf bank_mask:0xf bound_ctrl:1
	v_add_f32_dpp v234, v234, v234 row_mirror row_mask:0xf bank_mask:0xf bound_ctrl:1
	s_waitcnt lgkmcnt(1)
	v_pk_fma_f32 v[36:37], v[12:13], v[234:235], v[54:55] op_sel_hi:[1,0,1]
	v_pk_fma_f32 v[34:35], v[10:11], v[234:235], v[56:57] op_sel_hi:[1,0,1]
	v_add_f32_dpp v238, v238, v238 quad_perm:[2,3,0,1] row_mask:0xf bank_mask:0xf bound_ctrl:1
	ds_write_b32 v49, v238 offset:3584
	v_pk_mul_f32 v[236:237], v[8:9], v[36:37]
	v_pk_fma_f32 v[236:237], v[6:7], v[34:35], v[236:237]
	v_add_f32_e32 v238, v236, v237
	s_nop 1
	v_add_f32_dpp v52, v238, v238 quad_perm:[1,0,3,2] row_mask:0xf bank_mask:0xf bound_ctrl:1
	s_nop 1
	v_mov_b32_dpp v64, v52 quad_perm:[2,3,0,1] row_mask:0xf bank_mask:0xf bound_ctrl:1
	s_add_i32 s61, s57, 1
	s_and_b32 s62, s61, 0x7f
	s_add_i32 s62, s62, -1
	s_cmp_lt_u32 s62, 0x7e
	s_cselect_b32 s62, 1, 0
	s_cmp_lt_i32 s61, s38
	s_cselect_b32 s62, s62, 0
	s_cmp_lg_u32 s62, 0
	s_cbranch_scc0 .LBB0_1634
	v_add_f32_e32 v6, v52, v64
	v_add_u32_e32 v7, s2, v49
	ds_write_b32 v7, v6
	v_readlane_b32 s4, v253, 53
	v_readlane_b32 s5, v253, 2
	s_add_i32 s54, s54, s4
	s_add_i32 s60, s60, s5
	s_mov_b32 s57, s61
	s_addk_i32 s58, 0x1000
	s_addk_i32 s59, 0x4000
	s_and_b32 s3, s57, 3
	s_mov_b32 s2, s56
	s_mov_b64 s[26:27], 0
	s_waitcnt lgkmcnt(0)
	s_barrier
	s_branch .LBB0_1630

.LBB0_1654:
	s_lshr_b32 s2, s57, 7
	v_readlane_b32 s3, v253, 2
	s_mul_i32 s2, s2, s3
	v_readlane_b32 s3, v253, 3
	s_add_i32 s2, s2, s3
	s_ashr_i32 s4, s2, 6
	s_bfe_u32 s28, s2, 0x40002
	s_lshl_b32 s2, s2, 4
	s_and_b32 s3, s57, 0x7f
	s_and_b32 s2, s2, 48
	s_mov_b32 s56, s2
	s_cmpk_eq_i32 s3, 0x7f
	s_cselect_b64 s[26:27], -1, 0
	s_mov_b64 s[18:19], s[64:65]
	s_ashr_i32 s5, s4, 31
	s_lshl_b64 s[4:5], s[4:5], 4
	s_add_u32 s4, s4, s24
	s_addc_u32 s5, s5, s25
	s_or_b32 s4, s4, s28
	s_lshl_b64 s[4:5], s[4:5], 14
	s_waitcnt lgkmcnt(0)
	s_add_u32 s4, s18, s4
	s_addc_u32 s5, s19, s5
	s_lshl_b32 s18, s2, 8
	s_add_u32 s4, s4, s18
	s_addc_u32 s5, s5, 0
	s_add_u32 s28, s4, 0x4800000
	s_addc_u32 s29, s5, 0
	s_cmp_lg_u32 s3, 0
	s_cselect_b64 vcc, -1, 0
	v_cndmask_b32_e32 v37, 0, v5, vcc
	v_cndmask_b32_e32 v36, 0, v4, vcc
	v_cndmask_b32_e32 v35, 0, v3, vcc
	v_cndmask_b32_e32 v34, 0, v2, vcc
	s_and_b32 s3, s57, 3
	s_cbranch_execz .LBB0_1629
	s_branch .LBB0_1630
